# v112 + grid barrier: XCD leaders no longer write the (now unread) per-XCD relay word nor wait for the generation add before/after the invalidate
# baseline (speedup 1.0000x reference)
; __device__ __forceinline__ unsigned xb_ld(unsigned* p)              { return __hip_atomic_load(p, __ATOMIC_RELAXED, __HIP_MEMORY_SCOPE_AGENT); }
; __device__ __forceinline__ unsigned xb_add(unsigned* p, unsigned v) { return __hip_atomic_fetch_add(p, v, __ATOMIC_RELAXED, __HIP_MEMORY_SCOPE_AGENT); }
; #define XB_SPIN(cond, bar) do { unsigned _sp = 0; while (cond) { __builtin_amdgcn_s_sleep(1); \
;     if ((++_sp & 255u) == 0u) { if (xb_ld(&(bar)[XB_TMO])) break; if (_sp > XB_SPIN_CAP) { atomicAdd(&(bar)[XB_TMO], 1u); break; } } } } while (0)
; __device__ __forceinline__ void xcd_barrier(const XcdBarrier& b) {
;     ...
;         if (old + 1u == (gen + 1u) * nloc) {
;             __builtin_amdgcn_fence(__ATOMIC_RELEASE, "agent");
;             asm volatile("s_waitcnt vmcnt(0)" ::: "memory");
;             const unsigned og = xb_add(&bar[XB_TOP], 1u);
;             const unsigned tg = og / nx;
;             if (og + 1u == (tg + 1u) * nx) xb_add(&bar[XB_TOPGEN], 1u);
;             else XB_SPIN(xb_ld(&bar[XB_TOPGEN]) == tg, bar);
;             __builtin_amdgcn_fence(__ATOMIC_ACQUIRE, "agent");
;             xb_add(&bar[XB_XGEN(b.x)], 1u);
;             asm volatile("s_waitcnt vmcnt(0)" ::: "memory");
.LBB0_1250:
	s_or_b64 exec, exec, s[20:21]
	s_mov_b64 s[20:21], exec
	v_mbcnt_lo_u32_b32 v0, s20, 0
	v_mbcnt_hi_u32_b32 v0, s21, v0
	v_cmp_eq_u32_e32 vcc, 0, v0
	buffer_inv sc1
	s_and_saveexec_b64 s[22:23], vcc
	s_cbranch_execz .LBB0_1252
	s_bcnt1_i32_b64 s20, s[20:21]
	v_mov_b32_e32 v0, s20
	v_readlane_b32 s20, v252, 23
	v_readlane_b32 s21, v252, 24
	s_nop 4
.LBB0_1252:
	s_or_b64 exec, exec, s[22:23]
.LBB0_1253:
	s_or_b64 exec, exec, s[0:1]
	s_mov_b64 s[0:1], 0
	s_waitcnt lgkmcnt(0)
	s_barrier
